# attention unit epilogue: gain quads read three column groups ahead through a ring of four register quads, counted lgkmcnt waits (de-waterfalled LDS reads)
# speedup vs baseline: 1.0079x; 1.0034x over previous
; #define LAS __attribute__((address_space(3)))
; __device__ __forceinline__ void attn_unit(const TI ti, CArgs& a, int b, int hd, int qrow0, int st_lo, int st_hi, float mfix, float lam, float lam_init, const float* subg, unsigned char* ldsg) {
;     ...
;     const float ltot = lsum + __shfl_xor(lsum, 32);
;     const float linv = 1.f / ltot;
;     LAS float* X = (LAS float*)L + qt * 4096;
;     if (c == 1) {
; #pragma unroll
;         for (int e = 0; e < 4; ++e)
; #pragma unroll
;             for (int i = 0; i < 16; ++i) X[(e * 16 + i) * 64 + lane] = O[e][i] * linv;
;     }
;     __syncthreads();
;     if (c == 0) {
;         float ssq = 0.f;
; #pragma unroll
;         for (int e = 0; e < 4; ++e)
; #pragma unroll
;             for (int i = 0; i < 16; ++i) { const float o = O[e][i] * linv - lam * X[(e * 16 + i) * 64 + lane]; O[e][i] = o; ssq += o * o; }
.LBB0_346:
	s_or_b64 exec, exec, s[4:5]
	s_waitcnt lgkmcnt(0)
	s_barrier
	s_and_saveexec_b64 s[48:49], s[42:43]
	s_cbranch_execz .LBB0_348
	ds_read2st64_b32 v[90:91], v164 offset1:1
	ds_read2st64_b32 v[92:93], v164 offset0:2 offset1:3
	ds_read2st64_b32 v[94:95], v164 offset0:4 offset1:5
	ds_read2st64_b32 v[96:97], v164 offset0:6 offset1:7
	ds_read2st64_b32 v[98:99], v164 offset0:8 offset1:9
	ds_read2st64_b32 v[104:105], v164 offset0:10 offset1:11
	ds_read2st64_b32 v[108:109], v164 offset0:12 offset1:13
	ds_read2st64_b32 v[110:111], v164 offset0:14 offset1:15
	ds_read2st64_b32 v[112:113], v164 offset0:16 offset1:17
	ds_read2st64_b32 v[114:115], v164 offset0:18 offset1:19
	ds_read2st64_b32 v[116:117], v164 offset0:20 offset1:21
	ds_read2st64_b32 v[118:119], v164 offset0:22 offset1:23
	ds_read2st64_b32 v[120:121], v164 offset0:24 offset1:25
	ds_read2st64_b32 v[122:123], v164 offset0:26 offset1:27
	ds_read2st64_b32 v[124:125], v164 offset0:28 offset1:29
	ds_read2st64_b32 v[126:127], v164 offset0:30 offset1:31
	ds_read2st64_b32 v[128:129], v164 offset0:32 offset1:33
	ds_read2st64_b32 v[130:131], v164 offset0:34 offset1:35
	ds_read2st64_b32 v[132:133], v164 offset0:36 offset1:37
	ds_read2st64_b32 v[182:183], v164 offset0:38 offset1:39
	ds_read2st64_b32 v[184:185], v164 offset0:40 offset1:41
	ds_read2st64_b32 v[198:199], v164 offset0:42 offset1:43
	ds_read2st64_b32 v[200:201], v164 offset0:44 offset1:45
	ds_read2st64_b32 v[202:203], v164 offset0:46 offset1:47
	ds_read2st64_b32 v[204:205], v164 offset0:56 offset1:57
	ds_read2st64_b32 v[206:207], v164 offset0:58 offset1:59
	ds_read2st64_b32 v[82:83], v164 offset0:60 offset1:61
	ds_read2st64_b32 v[84:85], v164 offset0:62 offset1:63
	ds_read2st64_b32 v[208:209], v164 offset0:48 offset1:49
	ds_read2st64_b32 v[210:211], v164 offset0:50 offset1:51
	ds_read2st64_b32 v[212:213], v164 offset0:52 offset1:53
	ds_read2st64_b32 v[214:215], v164 offset0:54 offset1:55
	s_waitcnt lgkmcnt(14)
	v_pk_mul_f32 v[90:91], v[134:135], v[90:91]
	v_pk_mul_f32 v[92:93], v[134:135], v[92:93]
	v_pk_fma_f32 v[90:91], v[18:19], v[86:87], v[90:91] op_sel_hi:[1,0,1] neg_lo:[0,0,1] neg_hi:[0,0,1]
	v_pk_mul_f32 v[18:19], v[134:135], v[96:97]
	v_pk_fma_f32 v[20:21], v[20:21], v[86:87], v[92:93] op_sel_hi:[1,0,1] neg_lo:[0,0,1] neg_hi:[0,0,1]
	v_pk_fma_f32 v[92:93], v[24:25], v[86:87], v[18:19] op_sel_hi:[1,0,1] neg_lo:[0,0,1] neg_hi:[0,0,1]
	v_pk_mul_f32 v[18:19], v[134:135], v[94:95]
	s_waitcnt lgkmcnt(5)
	v_pk_mul_f32 v[82:83], v[134:135], v[82:83]
	v_pk_fma_f32 v[102:103], v[22:23], v[86:87], v[18:19] op_sel_hi:[1,0,1] neg_lo:[0,0,1] neg_hi:[0,0,1]
	v_pk_mul_f32 v[18:19], v[134:135], v[104:105]
	s_waitcnt lgkmcnt(1)
	v_pk_mul_f32 v[22:23], v[134:135], v[212:213]
	v_pk_fma_f32 v[94:95], v[28:29], v[86:87], v[18:19] op_sel_hi:[1,0,1] neg_lo:[0,0,1] neg_hi:[0,0,1]
	v_pk_mul_f32 v[18:19], v[134:135], v[98:99]
	v_pk_fma_f32 v[82:83], v[46:47], v[86:87], v[82:83] op_sel_hi:[1,0,1] neg_lo:[0,0,1] neg_hi:[0,0,1]
	v_pk_fma_f32 v[106:107], v[26:27], v[86:87], v[18:19] op_sel_hi:[1,0,1] neg_lo:[0,0,1] neg_hi:[0,0,1]
	v_pk_mul_f32 v[18:19], v[134:135], v[110:111]
	v_pk_mul_f32 v[46:47], v[134:135], v[84:85]
	v_pk_fma_f32 v[96:97], v[32:33], v[86:87], v[18:19] op_sel_hi:[1,0,1] neg_lo:[0,0,1] neg_hi:[0,0,1]
	v_pk_mul_f32 v[18:19], v[134:135], v[108:109]
	v_pk_mul_f32 v[218:219], v[90:91], v[90:91]
	v_pk_fma_f32 v[108:109], v[30:31], v[86:87], v[18:19] op_sel_hi:[1,0,1] neg_lo:[0,0,1] neg_hi:[0,0,1]
	v_pk_mul_f32 v[18:19], v[134:135], v[114:115]
	v_pk_fma_f32 v[84:85], v[48:49], v[86:87], v[46:47] op_sel_hi:[1,0,1] neg_lo:[0,0,1] neg_hi:[0,0,1]
	v_pk_fma_f32 v[98:99], v[68:69], v[86:87], v[18:19] op_sel_hi:[1,0,1] neg_lo:[0,0,1] neg_hi:[0,0,1]
	v_pk_mul_f32 v[18:19], v[134:135], v[112:113]
	ds_read_b128 v[46:49], v249
	v_pk_fma_f32 v[104:105], v[66:67], v[86:87], v[18:19] op_sel_hi:[1,0,1] neg_lo:[0,0,1] neg_hi:[0,0,1]
	v_pk_mul_f32 v[18:19], v[134:135], v[118:119]
	v_pk_mul_f32 v[216:217], v[20:21], v[20:21]
	v_pk_fma_f32 v[32:33], v[72:73], v[86:87], v[18:19] op_sel_hi:[1,0,1] neg_lo:[0,0,1] neg_hi:[0,0,1]
	v_pk_mul_f32 v[18:19], v[134:135], v[116:117]
	v_pk_mul_f32 v[222:223], v[102:103], v[102:103]
	v_pk_fma_f32 v[70:71], v[70:71], v[86:87], v[18:19] op_sel_hi:[1,0,1] neg_lo:[0,0,1] neg_hi:[0,0,1]
	v_pk_mul_f32 v[18:19], v[134:135], v[122:123]
	v_pk_mul_f32 v[220:221], v[92:93], v[92:93]
	v_pk_fma_f32 v[66:67], v[76:77], v[86:87], v[18:19] op_sel_hi:[1,0,1] neg_lo:[0,0,1] neg_hi:[0,0,1]
	v_pk_mul_f32 v[18:19], v[134:135], v[120:121]
	v_pk_mul_f32 v[226:227], v[106:107], v[106:107]
	v_pk_fma_f32 v[72:73], v[74:75], v[86:87], v[18:19] op_sel_hi:[1,0,1] neg_lo:[0,0,1] neg_hi:[0,0,1]
	v_pk_mul_f32 v[18:19], v[134:135], v[126:127]
	v_pk_mul_f32 v[224:225], v[94:95], v[94:95]
	v_pk_fma_f32 v[68:69], v[80:81], v[86:87], v[18:19] op_sel_hi:[1,0,1] neg_lo:[0,0,1] neg_hi:[0,0,1]
	v_pk_mul_f32 v[18:19], v[134:135], v[124:125]
	v_pk_mul_f32 v[228:229], v[108:109], v[108:109]
	v_pk_fma_f32 v[74:75], v[78:79], v[86:87], v[18:19] op_sel_hi:[1,0,1] neg_lo:[0,0,1] neg_hi:[0,0,1]
	v_pk_mul_f32 v[18:19], v[134:135], v[130:131]
	v_pk_mul_f32 v[110:111], v[96:97], v[96:97]
	v_pk_fma_f32 v[52:53], v[52:53], v[86:87], v[18:19] op_sel_hi:[1,0,1] neg_lo:[0,0,1] neg_hi:[0,0,1]
	v_pk_mul_f32 v[18:19], v[134:135], v[128:129]
	v_pk_mul_f32 v[112:113], v[104:105], v[104:105]
	v_pk_fma_f32 v[50:51], v[50:51], v[86:87], v[18:19] op_sel_hi:[1,0,1] neg_lo:[0,0,1] neg_hi:[0,0,1]
	v_pk_mul_f32 v[18:19], v[134:135], v[182:183]
	v_pk_mul_f32 v[114:115], v[98:99], v[98:99]
	v_pk_fma_f32 v[24:25], v[56:57], v[86:87], v[18:19] op_sel_hi:[1,0,1] neg_lo:[0,0,1] neg_hi:[0,0,1]
; __device__ __forceinline__ unsigned pkbf(float lo, float hi) { f32x2 v = {lo, hi}; bf16x2v b = __builtin_convertvector(v, bf16x2v); return __builtin_bit_cast(unsigned, b); }
; __device__ __forceinline__ void attn_unit(const TI ti, CArgs& a, int b, int hd, int qrow0, int st_lo, int st_hi, float mfix, float lam, float lam_init, const float* subg, unsigned char* ldsg) {
;     ...
;         float ssq = 0.f;
; #pragma unroll
;         for (int e = 0; e < 4; ++e)
; #pragma unroll
;             for (int i = 0; i < 16; ++i) { const float o = O[e][i] * linv - lam * X[(e * 16 + i) * 64 + lane]; O[e][i] = o; ssq += o * o; }
;         ssq += __shfl_xor(ssq, 32);
;         const float sc = rsqrtf(ssq * (1.f / 128.f) + 1e-6f) * (1.f - lam_init);
;         bf16_t* op = Qb + (size_t)(qrow0 + qt * 32 + r) * 1024 + hd * 128;
; #pragma unroll
;         for (int e = 0; e < 4; ++e)
; #pragma unroll
;             for (int g4 = 0; g4 < 4; ++g4) {
;                 const int e0 = e * 32 + 8 * g4 + 4 * h; const f32x4 sg = *(const f32x4*)(subg + e0);
;                 u32x2 o; o.x = pkbf(O[e][4 * g4 + 0] * sc * sg.x, O[e][4 * g4 + 1] * sc * sg.y); o.y = pkbf(O[e][4 * g4 + 2] * sc * sg.z, O[e][4 * g4 + 3] * sc * sg.w);
	v_pk_mul_f32 v[18:19], v[134:135], v[132:133]
	v_pk_mul_f32 v[116:117], v[70:71], v[70:71]
	v_pk_fma_f32 v[54:55], v[54:55], v[86:87], v[18:19] op_sel_hi:[1,0,1] neg_lo:[0,0,1] neg_hi:[0,0,1]
	v_pk_mul_f32 v[18:19], v[134:135], v[198:199]
	v_pk_mul_f32 v[118:119], v[32:33], v[32:33]
	v_pk_fma_f32 v[26:27], v[60:61], v[86:87], v[18:19] op_sel_hi:[1,0,1] neg_lo:[0,0,1] neg_hi:[0,0,1]
	v_pk_mul_f32 v[18:19], v[134:135], v[184:185]
	v_pk_mul_f32 v[120:121], v[72:73], v[72:73]
	v_pk_fma_f32 v[56:57], v[58:59], v[86:87], v[18:19] op_sel_hi:[1,0,1] neg_lo:[0,0,1] neg_hi:[0,0,1]
	v_pk_mul_f32 v[18:19], v[134:135], v[202:203]
	v_pk_mul_f32 v[76:77], v[66:67], v[66:67]
	v_pk_fma_f32 v[28:29], v[64:65], v[86:87], v[18:19] op_sel_hi:[1,0,1] neg_lo:[0,0,1] neg_hi:[0,0,1]
	v_pk_mul_f32 v[18:19], v[134:135], v[200:201]
	v_pk_mul_f32 v[78:79], v[74:75], v[74:75]
	v_pk_fma_f32 v[58:59], v[62:63], v[86:87], v[18:19] op_sel_hi:[1,0,1] neg_lo:[0,0,1] neg_hi:[0,0,1]
	v_pk_mul_f32 v[18:19], v[134:135], v[210:211]
	v_pk_mul_f32 v[80:81], v[68:69], v[68:69]
	v_pk_fma_f32 v[30:31], v[36:37], v[86:87], v[18:19] op_sel_hi:[1,0,1] neg_lo:[0,0,1] neg_hi:[0,0,1]
	v_pk_mul_f32 v[18:19], v[134:135], v[208:209]
	v_pk_fma_f32 v[36:37], v[38:39], v[86:87], v[22:23] op_sel_hi:[1,0,1] neg_lo:[0,0,1] neg_hi:[0,0,1]
	v_pk_fma_f32 v[34:35], v[34:35], v[86:87], v[18:19] op_sel_hi:[1,0,1] neg_lo:[0,0,1] neg_hi:[0,0,1]
	s_waitcnt lgkmcnt(0)
	v_pk_mul_f32 v[18:19], v[134:135], v[214:215]
	v_pk_mul_f32 v[22:23], v[134:135], v[206:207]
	v_pk_mul_f32 v[38:39], v[134:135], v[204:205]
	v_pk_fma_f32 v[18:19], v[40:41], v[86:87], v[18:19] op_sel_hi:[1,0,1] neg_lo:[0,0,1] neg_hi:[0,0,1]
	v_pk_fma_f32 v[22:23], v[44:45], v[86:87], v[22:23] op_sel_hi:[1,0,1] neg_lo:[0,0,1] neg_hi:[0,0,1]
	v_pk_fma_f32 v[38:39], v[42:43], v[86:87], v[38:39] op_sel_hi:[1,0,1] neg_lo:[0,0,1] neg_hi:[0,0,1]
	v_add_f32_e32 v86, v218, v219
	v_add_f32_e32 v86, v86, v216
	v_add_f32_e32 v86, v86, v217
	v_add_f32_e32 v86, v86, v222
	v_add_f32_e32 v86, v86, v223
	v_add_f32_e32 v86, v86, v220
	v_add_f32_e32 v86, v86, v221
	v_add_f32_e32 v86, v86, v226
	v_add_f32_e32 v86, v86, v227
	v_add_f32_e32 v86, v86, v224
	v_add_f32_e32 v86, v86, v225
	v_add_f32_e32 v86, v86, v228
	v_add_f32_e32 v86, v86, v229
	v_add_f32_e32 v86, v86, v110
	v_add_f32_e32 v86, v86, v111
	v_add_f32_e32 v86, v86, v112
	v_add_f32_e32 v86, v86, v113
	v_add_f32_e32 v86, v86, v114
	v_add_f32_e32 v86, v86, v115
	v_add_f32_e32 v86, v86, v116
	v_add_f32_e32 v86, v86, v117
	v_add_f32_e32 v86, v86, v118
	v_add_f32_e32 v86, v86, v119
	v_add_f32_e32 v86, v86, v120
	v_add_f32_e32 v86, v86, v121
	v_add_f32_e32 v76, v86, v76
	v_add_f32_e32 v76, v76, v77
	v_add_f32_e32 v76, v76, v78
	v_add_f32_e32 v76, v76, v79
	v_add_f32_e32 v76, v76, v80
	v_pk_mul_f32 v[124:125], v[50:51], v[50:51]
	v_add_f32_e32 v76, v76, v81
	v_add_f32_e32 v76, v76, v124
	v_pk_mul_f32 v[122:123], v[52:53], v[52:53]
	v_add_f32_e32 v76, v76, v125
	v_add_f32_e32 v76, v76, v122
	v_pk_mul_f32 v[128:129], v[54:55], v[54:55]
	v_add_f32_e32 v76, v76, v123
	v_add_f32_e32 v76, v76, v128
	v_pk_mul_f32 v[126:127], v[24:25], v[24:25]
	v_add_f32_e32 v76, v76, v129
	v_add_f32_e32 v76, v76, v126
	v_pk_mul_f32 v[130:131], v[56:57], v[56:57]
	v_add_f32_e32 v76, v76, v127
	v_add_f32_e32 v76, v76, v130
	v_pk_mul_f32 v[60:61], v[26:27], v[26:27]
	v_add_f32_e32 v76, v76, v131
	v_add_f32_e32 v60, v76, v60
	v_pk_mul_f32 v[62:63], v[58:59], v[58:59]
	v_add_f32_e32 v60, v60, v61
	v_add_f32_e32 v60, v60, v62
	v_pk_mul_f32 v[64:65], v[28:29], v[28:29]
	v_add_f32_e32 v60, v60, v63
	v_add_f32_e32 v60, v60, v64
	v_pk_mul_f32 v[182:183], v[34:35], v[34:35]
	v_add_f32_e32 v60, v60, v65
	v_add_f32_e32 v60, v60, v182
	v_pk_mul_f32 v[132:133], v[30:31], v[30:31]
	v_add_f32_e32 v60, v60, v183
	v_add_f32_e32 v60, v60, v132
	v_pk_mul_f32 v[184:185], v[36:37], v[36:37]
	v_add_f32_e32 v60, v60, v133
	v_add_f32_e32 v60, v60, v184
	v_pk_mul_f32 v[40:41], v[18:19], v[18:19]
	v_add_f32_e32 v60, v60, v185
	v_add_f32_e32 v40, v60, v40
	v_pk_mul_f32 v[42:43], v[38:39], v[38:39]
	v_add_f32_e32 v40, v40, v41
	v_add_f32_e32 v40, v40, v42
	v_pk_mul_f32 v[44:45], v[22:23], v[22:23]
	v_add_f32_e32 v40, v40, v43
	v_add_f32_e32 v40, v40, v44
	v_pk_mul_f32 v[88:89], v[82:83], v[82:83]
	v_add_f32_e32 v40, v40, v45
	v_add_f32_e32 v40, v40, v88
	v_pk_mul_f32 v[100:101], v[84:85], v[84:85]
	v_add_f32_e32 v40, v40, v89
	v_add_f32_e32 v40, v40, v100
	v_add_f32_e32 v40, v40, v101
	ds_bpermute_b32 v41, v137, v40
	s_waitcnt lgkmcnt(0)
	v_add_f32_e32 v40, v40, v41
	v_fmamk_f32 v40, v40, 0x3c000000, v172
	v_mul_f32_e32 v41, 0x4b800000, v40
	v_cmp_gt_f32_e32 vcc, s8, v40
	s_nop 1
	v_cndmask_b32_e32 v40, v40, v41, vcc
	v_rsq_f32_e32 v42, v40
	v_lshlrev_b32_e32 v40, 2, v146
	v_mov_b32_e32 v41, v1
	v_lshl_add_u64 v[44:45], v[152:153], 0, v[40:41]
	v_mul_f32_e32 v40, 0x45800000, v42
	v_cndmask_b32_e32 v40, v42, v40, vcc
	v_mul_f32_e32 v60, v165, v40
	v_pk_mul_f32 v[40:41], v[90:91], v[60:61] op_sel_hi:[1,0]
	v_pk_mul_f32 v[20:21], v[20:21], v[60:61] op_sel_hi:[1,0]
	s_waitcnt lgkmcnt(0)
	ds_read_b128 v[234:237], v249 offset:32
	ds_read_b128 v[238:241], v249 offset:64
	ds_read_b128 v[242:245], v249 offset:96
	v_pk_mul_f32 v[40:41], v[46:47], v[40:41]
	v_pk_mul_f32 v[20:21], v[48:49], v[20:21]
	v_cvt_pk_bf16_f32 v250, v40, v41
	v_cvt_pk_bf16_f32 v251, v20, v21
	ds_read_b128 v[230:233], v249 offset:128
	v_pk_mul_f32 v[20:21], v[102:103], v[60:61] op_sel_hi:[1,0]
	v_pk_mul_f32 v[46:47], v[94:95], v[60:61] op_sel_hi:[1,0]
	v_pk_mul_f32 v[32:33], v[32:33], v[60:61] op_sel_hi:[1,0]
	v_pk_mul_f32 v[24:25], v[24:25], v[60:61] op_sel_hi:[1,0]
	v_pk_mul_f32 v[28:29], v[28:29], v[60:61] op_sel_hi:[1,0]
	v_pk_mul_f32 v[18:19], v[18:19], v[60:61] op_sel_hi:[1,0]
	v_pk_mul_f32 v[22:23], v[22:23], v[60:61] op_sel_hi:[1,0]
	s_waitcnt lgkmcnt(3)
; __device__ __forceinline__ unsigned pkbf(float lo, float hi) { f32x2 v = {lo, hi}; bf16x2v b = __builtin_convertvector(v, bf16x2v); return __builtin_bit_cast(unsigned, b); }
; __device__ __forceinline__ void attn_unit(const TI ti, CArgs& a, int b, int hd, int qrow0, int st_lo, int st_hi, float mfix, float lam, float lam_init, const float* subg, unsigned char* ldsg) {
;     ...
; #pragma unroll
;         for (int e = 0; e < 4; ++e)
; #pragma unroll
;             for (int g4 = 0; g4 < 4; ++g4) {
;                 const int e0 = e * 32 + 8 * g4 + 4 * h; const f32x4 sg = *(const f32x4*)(subg + e0);
;                 u32x2 o; o.x = pkbf(O[e][4 * g4 + 0] * sc * sg.x, O[e][4 * g4 + 1] * sc * sg.y); o.y = pkbf(O[e][4 * g4 + 2] * sc * sg.z, O[e][4 * g4 + 3] * sc * sg.w);
;                 *(u32x2*)(op + e0) = o;
;             }
	v_pk_mul_f32 v[20:21], v[234:235], v[20:21]
	v_pk_mul_f32 v[40:41], v[92:93], v[60:61] op_sel_hi:[1,0]
	v_cvt_pk_bf16_f32 v252, v20, v21
	v_pk_mul_f32 v[40:41], v[236:237], v[40:41]
	s_nop 0
	v_cvt_pk_bf16_f32 v253, v40, v41
	s_nop 1
	v_permlane32_swap_b32 v250, v252
	v_permlane32_swap_b32 v251, v253
	s_nop 0
	global_store_dwordx4 v[44:45], v[250:253], off
	ds_read_b128 v[234:237], v249 offset:160
	v_pk_mul_f32 v[20:21], v[106:107], v[60:61] op_sel_hi:[1,0]
	s_waitcnt lgkmcnt(3)
	v_pk_mul_f32 v[20:21], v[238:239], v[20:21]
	v_pk_mul_f32 v[40:41], v[240:241], v[46:47]
	v_cvt_pk_bf16_f32 v250, v20, v21
	v_cvt_pk_bf16_f32 v251, v40, v41
	ds_read_b128 v[238:241], v249 offset:192
	v_pk_mul_f32 v[20:21], v[108:109], v[60:61] op_sel_hi:[1,0]
	v_pk_mul_f32 v[46:47], v[96:97], v[60:61] op_sel_hi:[1,0]
	s_waitcnt lgkmcnt(3)
	v_pk_mul_f32 v[20:21], v[242:243], v[20:21]
	v_pk_mul_f32 v[40:41], v[244:245], v[46:47]
	v_cvt_pk_bf16_f32 v252, v20, v21
	v_cvt_pk_bf16_f32 v253, v40, v41
	s_nop 1
	v_permlane32_swap_b32 v250, v252
	v_permlane32_swap_b32 v251, v253
	s_nop 0
	global_store_dwordx4 v[44:45], v[250:253], off offset:32
	ds_read_b128 v[242:245], v249 offset:224
	v_pk_mul_f32 v[20:21], v[104:105], v[60:61] op_sel_hi:[1,0]
	v_pk_mul_f32 v[46:47], v[98:99], v[60:61] op_sel_hi:[1,0]
	s_waitcnt lgkmcnt(3)
	v_pk_mul_f32 v[20:21], v[230:231], v[20:21]
	v_pk_mul_f32 v[40:41], v[232:233], v[46:47]
	v_cvt_pk_bf16_f32 v250, v20, v21
	v_cvt_pk_bf16_f32 v251, v40, v41
	ds_read_b128 v[230:233], v249 offset:256
	v_pk_mul_f32 v[20:21], v[70:71], v[60:61] op_sel_hi:[1,0]
	s_waitcnt lgkmcnt(3)
	v_pk_mul_f32 v[32:33], v[236:237], v[32:33]
	v_pk_mul_f32 v[20:21], v[234:235], v[20:21]
	s_nop 0
	v_cvt_pk_bf16_f32 v252, v20, v21
	v_cvt_pk_bf16_f32 v253, v32, v33
	s_nop 1
	v_permlane32_swap_b32 v250, v252
	v_permlane32_swap_b32 v251, v253
	s_nop 0
	global_store_dwordx4 v[44:45], v[250:253], off offset:64
	ds_read_b128 v[234:237], v249 offset:288
	v_pk_mul_f32 v[20:21], v[72:73], v[60:61] op_sel_hi:[1,0]
	v_pk_mul_f32 v[32:33], v[66:67], v[60:61] op_sel_hi:[1,0]
	s_waitcnt lgkmcnt(3)
	v_pk_mul_f32 v[20:21], v[238:239], v[20:21]
	v_pk_mul_f32 v[32:33], v[240:241], v[32:33]
	v_cvt_pk_bf16_f32 v250, v20, v21
	v_cvt_pk_bf16_f32 v251, v32, v33
	ds_read_b128 v[238:241], v249 offset:320
	v_pk_mul_f32 v[20:21], v[74:75], v[60:61] op_sel_hi:[1,0]
	v_pk_mul_f32 v[32:33], v[68:69], v[60:61] op_sel_hi:[1,0]
	s_waitcnt lgkmcnt(3)
	v_pk_mul_f32 v[20:21], v[20:21], v[242:243]
	v_pk_mul_f32 v[32:33], v[32:33], v[244:245]
	v_cvt_pk_bf16_f32 v252, v20, v21
	v_cvt_pk_bf16_f32 v253, v32, v33
	s_nop 1
	v_permlane32_swap_b32 v250, v252
	v_permlane32_swap_b32 v251, v253
	s_nop 0
	global_store_dwordx4 v[44:45], v[250:253], off offset:96
	ds_read_b128 v[242:245], v249 offset:352
	v_pk_mul_f32 v[20:21], v[50:51], v[60:61] op_sel_hi:[1,0]
	v_pk_mul_f32 v[32:33], v[52:53], v[60:61] op_sel_hi:[1,0]
	s_waitcnt lgkmcnt(3)
	v_pk_mul_f32 v[20:21], v[20:21], v[230:231]
	v_pk_mul_f32 v[32:33], v[32:33], v[232:233]
	v_cvt_pk_bf16_f32 v250, v20, v21
	v_cvt_pk_bf16_f32 v251, v32, v33
	ds_read_b128 v[230:233], v249 offset:384
	v_pk_mul_f32 v[20:21], v[54:55], v[60:61] op_sel_hi:[1,0]
	s_waitcnt lgkmcnt(3)
	v_pk_mul_f32 v[24:25], v[24:25], v[236:237]
	v_pk_mul_f32 v[20:21], v[20:21], v[234:235]
	s_nop 0
	v_cvt_pk_bf16_f32 v252, v20, v21
	v_cvt_pk_bf16_f32 v253, v24, v25
	s_nop 1
	v_permlane32_swap_b32 v250, v252
	v_permlane32_swap_b32 v251, v253
	s_nop 0
	global_store_dwordx4 v[44:45], v[250:253], off offset:128
	ds_read_b128 v[234:237], v249 offset:416
	v_pk_mul_f32 v[20:21], v[56:57], v[60:61] op_sel_hi:[1,0]
	v_pk_mul_f32 v[24:25], v[26:27], v[60:61] op_sel_hi:[1,0]
	s_waitcnt lgkmcnt(3)
	v_pk_mul_f32 v[20:21], v[20:21], v[238:239]
	v_pk_mul_f32 v[24:25], v[24:25], v[240:241]
	v_cvt_pk_bf16_f32 v250, v20, v21
	v_cvt_pk_bf16_f32 v251, v24, v25
	ds_read_b128 v[238:241], v249 offset:448
	v_pk_mul_f32 v[20:21], v[58:59], v[60:61] op_sel_hi:[1,0]
	s_waitcnt lgkmcnt(3)
	v_pk_mul_f32 v[20:21], v[20:21], v[242:243]
	v_pk_mul_f32 v[24:25], v[28:29], v[244:245]
	v_cvt_pk_bf16_f32 v252, v20, v21
	v_cvt_pk_bf16_f32 v253, v24, v25
	s_nop 1
	v_permlane32_swap_b32 v250, v252
	v_permlane32_swap_b32 v251, v253
	s_nop 0
	global_store_dwordx4 v[44:45], v[250:253], off offset:160
	ds_read_b128 v[242:245], v249 offset:480
	v_pk_mul_f32 v[20:21], v[34:35], v[60:61] op_sel_hi:[1,0]
	v_pk_mul_f32 v[28:29], v[30:31], v[60:61] op_sel_hi:[1,0]
	s_waitcnt lgkmcnt(3)
	v_pk_mul_f32 v[20:21], v[20:21], v[230:231]
	v_pk_mul_f32 v[24:25], v[28:29], v[232:233]
	v_cvt_pk_bf16_f32 v250, v20, v21
	v_cvt_pk_bf16_f32 v251, v24, v25
	v_pk_mul_f32 v[20:21], v[36:37], v[60:61] op_sel_hi:[1,0]
	s_waitcnt lgkmcnt(2)
	v_pk_mul_f32 v[18:19], v[18:19], v[236:237]
	v_pk_mul_f32 v[20:21], v[20:21], v[234:235]
	v_pk_mul_f32 v[24:25], v[38:39], v[60:61] op_sel_hi:[1,0]
	v_cvt_pk_bf16_f32 v252, v20, v21
	v_cvt_pk_bf16_f32 v253, v18, v19
	s_nop 1
	v_permlane32_swap_b32 v250, v252
	v_permlane32_swap_b32 v251, v253
	s_nop 0
	global_store_dwordx4 v[44:45], v[250:253], off offset:192
	s_waitcnt lgkmcnt(1)
	v_pk_mul_f32 v[18:19], v[24:25], v[238:239]
	v_pk_mul_f32 v[20:21], v[22:23], v[240:241]
	v_cvt_pk_bf16_f32 v250, v18, v19
	v_cvt_pk_bf16_f32 v251, v20, v21
	v_pk_mul_f32 v[22:23], v[82:83], v[60:61] op_sel_hi:[1,0]
	v_pk_mul_f32 v[24:25], v[84:85], v[60:61] op_sel_hi:[1,0]
	s_waitcnt lgkmcnt(0)
	v_pk_mul_f32 v[18:19], v[22:23], v[242:243]
	v_pk_mul_f32 v[20:21], v[24:25], v[244:245]
	v_cvt_pk_bf16_f32 v252, v18, v19
	v_cvt_pk_bf16_f32 v253, v20, v21
	s_nop 1
	v_permlane32_swap_b32 v250, v252
	v_permlane32_swap_b32 v251, v253
	s_nop 0
	global_store_dwordx4 v[44:45], v[250:253], off offset:224

; __device__ __forceinline__ void attn_unit(const TI ti, CArgs& a, int b, int hd, int qrow0, int st_lo, int st_hi, float mfix, float lam, float lam_init, const float* subg, unsigned char* ldsg) {
;     ...
;     if (c == 0) {
;         float ssq = 0.f;
; #pragma unroll
;         for (int e = 0; e < 4; ++e)
; #pragma unroll
;             for (int i = 0; i < 16; ++i) { const float o = O[e][i] * linv - lam * X[(e * 16 + i) * 64 + lane]; O[e][i] = o; ssq += o * o; }
.LBB0_362:
	s_or_b64 exec, exec, s[4:5]
	s_waitcnt lgkmcnt(0)
	s_barrier
	s_and_saveexec_b64 s[48:49], s[42:43]
	s_cbranch_execz .LBB0_331
	ds_read2st64_b32 v[88:89], v164 offset1:1
	ds_read2st64_b32 v[90:91], v164 offset0:2 offset1:3
	ds_read2st64_b32 v[92:93], v164 offset0:4 offset1:5
	ds_read2st64_b32 v[94:95], v164 offset0:6 offset1:7
	ds_read2st64_b32 v[96:97], v164 offset0:8 offset1:9
	ds_read2st64_b32 v[102:103], v164 offset0:10 offset1:11
	ds_read2st64_b32 v[104:105], v164 offset0:12 offset1:13
	ds_read2st64_b32 v[106:107], v164 offset0:14 offset1:15
	ds_read2st64_b32 v[108:109], v164 offset0:16 offset1:17
	ds_read2st64_b32 v[114:115], v164 offset0:18 offset1:19
	ds_read2st64_b32 v[116:117], v164 offset0:20 offset1:21
	ds_read2st64_b32 v[118:119], v164 offset0:22 offset1:23
	ds_read2st64_b32 v[120:121], v164 offset0:24 offset1:25
	ds_read2st64_b32 v[122:123], v164 offset0:26 offset1:27
	ds_read2st64_b32 v[124:125], v164 offset0:28 offset1:29
	ds_read2st64_b32 v[126:127], v164 offset0:30 offset1:31
	ds_read2st64_b32 v[128:129], v164 offset0:32 offset1:33
	ds_read2st64_b32 v[130:131], v164 offset0:34 offset1:35
	ds_read2st64_b32 v[132:133], v164 offset0:36 offset1:37
	ds_read2st64_b32 v[150:151], v164 offset0:38 offset1:39
	ds_read2st64_b32 v[170:171], v164 offset0:40 offset1:41
	ds_read2st64_b32 v[182:183], v164 offset0:42 offset1:43
	ds_read2st64_b32 v[184:185], v164 offset0:44 offset1:45
	ds_read2st64_b32 v[198:199], v164 offset0:46 offset1:47
	ds_read2st64_b32 v[200:201], v164 offset0:56 offset1:57
	ds_read2st64_b32 v[202:203], v164 offset0:58 offset1:59
	ds_read2st64_b32 v[82:83], v164 offset0:60 offset1:61
	ds_read2st64_b32 v[84:85], v164 offset0:62 offset1:63
	ds_read2st64_b32 v[204:205], v164 offset0:48 offset1:49
	ds_read2st64_b32 v[206:207], v164 offset0:50 offset1:51
	ds_read2st64_b32 v[208:209], v164 offset0:52 offset1:53
	ds_read2st64_b32 v[210:211], v164 offset0:54 offset1:55
	s_waitcnt lgkmcnt(14)
	v_pk_mul_f32 v[88:89], v[134:135], v[88:89]
	v_pk_mul_f32 v[90:91], v[134:135], v[90:91]
	v_pk_fma_f32 v[88:89], v[18:19], v[0:1], v[88:89] op_sel_hi:[1,0,1] neg_lo:[0,0,1] neg_hi:[0,0,1]
	v_pk_mul_f32 v[18:19], v[134:135], v[94:95]
	v_pk_fma_f32 v[20:21], v[20:21], v[0:1], v[90:91] op_sel_hi:[1,0,1] neg_lo:[0,0,1] neg_hi:[0,0,1]
	v_pk_fma_f32 v[90:91], v[24:25], v[0:1], v[18:19] op_sel_hi:[1,0,1] neg_lo:[0,0,1] neg_hi:[0,0,1]
	v_pk_mul_f32 v[18:19], v[134:135], v[92:93]
	s_waitcnt lgkmcnt(5)
	v_pk_mul_f32 v[82:83], v[134:135], v[82:83]
	v_pk_fma_f32 v[100:101], v[22:23], v[0:1], v[18:19] op_sel_hi:[1,0,1] neg_lo:[0,0,1] neg_hi:[0,0,1]
	v_pk_mul_f32 v[18:19], v[134:135], v[102:103]
	s_waitcnt lgkmcnt(1)
	v_pk_mul_f32 v[22:23], v[134:135], v[208:209]
	v_pk_fma_f32 v[92:93], v[28:29], v[0:1], v[18:19] op_sel_hi:[1,0,1] neg_lo:[0,0,1] neg_hi:[0,0,1]
	v_pk_mul_f32 v[18:19], v[134:135], v[96:97]
	v_pk_fma_f32 v[82:83], v[62:63], v[0:1], v[82:83] op_sel_hi:[1,0,1] neg_lo:[0,0,1] neg_hi:[0,0,1]
	v_pk_fma_f32 v[110:111], v[26:27], v[0:1], v[18:19] op_sel_hi:[1,0,1] neg_lo:[0,0,1] neg_hi:[0,0,1]
	v_pk_mul_f32 v[18:19], v[134:135], v[106:107]
	v_pk_mul_f32 v[62:63], v[134:135], v[84:85]
	v_pk_fma_f32 v[94:95], v[32:33], v[0:1], v[18:19] op_sel_hi:[1,0,1] neg_lo:[0,0,1] neg_hi:[0,0,1]
	v_pk_mul_f32 v[18:19], v[134:135], v[104:105]
	v_pk_mul_f32 v[214:215], v[88:89], v[88:89]
	v_pk_fma_f32 v[112:113], v[30:31], v[0:1], v[18:19] op_sel_hi:[1,0,1] neg_lo:[0,0,1] neg_hi:[0,0,1]
	v_pk_mul_f32 v[18:19], v[134:135], v[114:115]
	v_pk_fma_f32 v[84:85], v[64:65], v[0:1], v[62:63] op_sel_hi:[1,0,1] neg_lo:[0,0,1] neg_hi:[0,0,1]
	v_pk_fma_f32 v[96:97], v[36:37], v[0:1], v[18:19] op_sel_hi:[1,0,1] neg_lo:[0,0,1] neg_hi:[0,0,1]
	v_pk_mul_f32 v[18:19], v[134:135], v[108:109]
	ds_read_b128 v[62:65], v249
	v_pk_fma_f32 v[102:103], v[34:35], v[0:1], v[18:19] op_sel_hi:[1,0,1] neg_lo:[0,0,1] neg_hi:[0,0,1]
	v_pk_mul_f32 v[18:19], v[134:135], v[118:119]
	v_pk_mul_f32 v[212:213], v[20:21], v[20:21]
	v_pk_fma_f32 v[32:33], v[40:41], v[0:1], v[18:19] op_sel_hi:[1,0,1] neg_lo:[0,0,1] neg_hi:[0,0,1]
	v_pk_mul_f32 v[18:19], v[134:135], v[116:117]
	v_pk_mul_f32 v[218:219], v[100:101], v[100:101]
	v_pk_fma_f32 v[104:105], v[38:39], v[0:1], v[18:19] op_sel_hi:[1,0,1] neg_lo:[0,0,1] neg_hi:[0,0,1]
	v_pk_mul_f32 v[18:19], v[134:135], v[122:123]
	v_pk_mul_f32 v[216:217], v[90:91], v[90:91]
	v_pk_fma_f32 v[34:35], v[44:45], v[0:1], v[18:19] op_sel_hi:[1,0,1] neg_lo:[0,0,1] neg_hi:[0,0,1]
	v_pk_mul_f32 v[18:19], v[134:135], v[120:121]
	v_pk_mul_f32 v[44:45], v[134:135], v[200:201]
	v_pk_fma_f32 v[106:107], v[42:43], v[0:1], v[18:19] op_sel_hi:[1,0,1] neg_lo:[0,0,1] neg_hi:[0,0,1]
	v_pk_mul_f32 v[18:19], v[134:135], v[126:127]
	v_pk_fma_f32 v[42:43], v[54:55], v[0:1], v[22:23] op_sel_hi:[1,0,1] neg_lo:[0,0,1] neg_hi:[0,0,1]
	v_pk_fma_f32 v[36:37], v[48:49], v[0:1], v[18:19] op_sel_hi:[1,0,1] neg_lo:[0,0,1] neg_hi:[0,0,1]
	v_pk_mul_f32 v[18:19], v[134:135], v[124:125]
	v_pk_mul_f32 v[22:23], v[134:135], v[202:203]
	v_pk_fma_f32 v[108:109], v[46:47], v[0:1], v[18:19] op_sel_hi:[1,0,1] neg_lo:[0,0,1] neg_hi:[0,0,1]
	v_pk_mul_f32 v[18:19], v[134:135], v[130:131]
	v_pk_fma_f32 v[22:23], v[60:61], v[0:1], v[22:23] op_sel_hi:[1,0,1] neg_lo:[0,0,1] neg_hi:[0,0,1]
	v_pk_fma_f32 v[38:39], v[68:69], v[0:1], v[18:19] op_sel_hi:[1,0,1] neg_lo:[0,0,1] neg_hi:[0,0,1]
	v_pk_mul_f32 v[18:19], v[134:135], v[128:129]
	v_pk_fma_f32 v[44:45], v[58:59], v[0:1], v[44:45] op_sel_hi:[1,0,1] neg_lo:[0,0,1] neg_hi:[0,0,1]
	v_pk_fma_f32 v[46:47], v[66:67], v[0:1], v[18:19] op_sel_hi:[1,0,1] neg_lo:[0,0,1] neg_hi:[0,0,1]
	v_pk_mul_f32 v[18:19], v[134:135], v[150:151]
	v_pk_mul_f32 v[222:223], v[110:111], v[110:111]
; __device__ __forceinline__ unsigned pkbf(float lo, float hi) { f32x2 v = {lo, hi}; bf16x2v b = __builtin_convertvector(v, bf16x2v); return __builtin_bit_cast(unsigned, b); }
; __device__ __forceinline__ void attn_unit(const TI ti, CArgs& a, int b, int hd, int qrow0, int st_lo, int st_hi, float mfix, float lam, float lam_init, const float* subg, unsigned char* ldsg) {
;     ...
;         float ssq = 0.f;
; #pragma unroll
;         for (int e = 0; e < 4; ++e)
; #pragma unroll
;             for (int i = 0; i < 16; ++i) { const float o = O[e][i] * linv - lam * X[(e * 16 + i) * 64 + lane]; O[e][i] = o; ssq += o * o; }
;         ssq += __shfl_xor(ssq, 32);
;         const float sc = rsqrtf(ssq * (1.f / 128.f) + 1e-6f) * (1.f - lam_init);
;         bf16_t* op = Qb + (size_t)(qrow0 + qt * 32 + r) * 1024 + hd * 128;
; #pragma unroll
;         for (int e = 0; e < 4; ++e)
; #pragma unroll
;             for (int g4 = 0; g4 < 4; ++g4) {
;                 const int e0 = e * 32 + 8 * g4 + 4 * h; const f32x4 sg = *(const f32x4*)(subg + e0);
;                 u32x2 o; o.x = pkbf(O[e][4 * g4 + 0] * sc * sg.x, O[e][4 * g4 + 1] * sc * sg.y); o.y = pkbf(O[e][4 * g4 + 2] * sc * sg.z, O[e][4 * g4 + 3] * sc * sg.w);
	v_pk_fma_f32 v[24:25], v[72:73], v[0:1], v[18:19] op_sel_hi:[1,0,1] neg_lo:[0,0,1] neg_hi:[0,0,1]
	v_pk_mul_f32 v[18:19], v[134:135], v[132:133]
	v_pk_mul_f32 v[220:221], v[92:93], v[92:93]
	v_pk_fma_f32 v[48:49], v[70:71], v[0:1], v[18:19] op_sel_hi:[1,0,1] neg_lo:[0,0,1] neg_hi:[0,0,1]
	v_pk_mul_f32 v[18:19], v[134:135], v[182:183]
	v_pk_mul_f32 v[226:227], v[112:113], v[112:113]
	v_pk_fma_f32 v[26:27], v[76:77], v[0:1], v[18:19] op_sel_hi:[1,0,1] neg_lo:[0,0,1] neg_hi:[0,0,1]
	v_pk_mul_f32 v[18:19], v[134:135], v[170:171]
	v_pk_mul_f32 v[224:225], v[94:95], v[94:95]
	v_pk_fma_f32 v[66:67], v[74:75], v[0:1], v[18:19] op_sel_hi:[1,0,1] neg_lo:[0,0,1] neg_hi:[0,0,1]
	v_pk_mul_f32 v[18:19], v[134:135], v[198:199]
	v_pk_mul_f32 v[228:229], v[102:103], v[102:103]
	v_pk_fma_f32 v[28:29], v[80:81], v[0:1], v[18:19] op_sel_hi:[1,0,1] neg_lo:[0,0,1] neg_hi:[0,0,1]
	v_pk_mul_f32 v[18:19], v[134:135], v[184:185]
	v_pk_mul_f32 v[114:115], v[96:97], v[96:97]
	v_pk_fma_f32 v[68:69], v[78:79], v[0:1], v[18:19] op_sel_hi:[1,0,1] neg_lo:[0,0,1] neg_hi:[0,0,1]
	v_pk_mul_f32 v[18:19], v[134:135], v[206:207]
	v_pk_mul_f32 v[116:117], v[104:105], v[104:105]
	v_pk_fma_f32 v[30:31], v[52:53], v[0:1], v[18:19] op_sel_hi:[1,0,1] neg_lo:[0,0,1] neg_hi:[0,0,1]
	v_pk_mul_f32 v[18:19], v[134:135], v[204:205]
	v_pk_mul_f32 v[118:119], v[32:33], v[32:33]
	v_pk_fma_f32 v[40:41], v[50:51], v[0:1], v[18:19] op_sel_hi:[1,0,1] neg_lo:[0,0,1] neg_hi:[0,0,1]
	s_waitcnt lgkmcnt(0)
	v_pk_mul_f32 v[18:19], v[134:135], v[210:211]
	v_pk_mul_f32 v[120:121], v[106:107], v[106:107]
	v_pk_fma_f32 v[18:19], v[56:57], v[0:1], v[18:19] op_sel_hi:[1,0,1] neg_lo:[0,0,1] neg_hi:[0,0,1]
	v_add_f32_e32 v0, v214, v215
	v_add_f32_e32 v0, v0, v212
	v_add_f32_e32 v0, v0, v213
	v_add_f32_e32 v0, v0, v218
	v_add_f32_e32 v0, v0, v219
	v_add_f32_e32 v0, v0, v216
	v_add_f32_e32 v0, v0, v217
	v_add_f32_e32 v0, v0, v222
	v_add_f32_e32 v0, v0, v223
	v_add_f32_e32 v0, v0, v220
	v_add_f32_e32 v0, v0, v221
	v_add_f32_e32 v0, v0, v226
	v_add_f32_e32 v0, v0, v227
	v_add_f32_e32 v0, v0, v224
	v_add_f32_e32 v0, v0, v225
	v_add_f32_e32 v0, v0, v228
	v_add_f32_e32 v0, v0, v229
	v_add_f32_e32 v0, v0, v114
	v_add_f32_e32 v0, v0, v115
	v_add_f32_e32 v0, v0, v116
	v_add_f32_e32 v0, v0, v117
	v_add_f32_e32 v0, v0, v118
	v_add_f32_e32 v0, v0, v119
	v_add_f32_e32 v0, v0, v120
	v_pk_mul_f32 v[122:123], v[34:35], v[34:35]
	v_add_f32_e32 v0, v0, v121
	v_add_f32_e32 v0, v0, v122
	v_pk_mul_f32 v[124:125], v[108:109], v[108:109]
	v_add_f32_e32 v0, v0, v123
	v_add_f32_e32 v0, v0, v124
	v_pk_mul_f32 v[126:127], v[36:37], v[36:37]
	v_add_f32_e32 v0, v0, v125
	v_add_f32_e32 v0, v0, v126
	v_pk_mul_f32 v[128:129], v[46:47], v[46:47]
	v_add_f32_e32 v0, v0, v127
	v_add_f32_e32 v0, v0, v128
	v_pk_mul_f32 v[130:131], v[38:39], v[38:39]
	v_add_f32_e32 v0, v0, v129
	v_add_f32_e32 v0, v0, v130
	v_pk_mul_f32 v[70:71], v[48:49], v[48:49]
	v_add_f32_e32 v0, v0, v131
	v_add_f32_e32 v0, v0, v70
	v_pk_mul_f32 v[72:73], v[24:25], v[24:25]
	v_add_f32_e32 v0, v0, v71
	v_add_f32_e32 v0, v0, v72
	v_pk_mul_f32 v[74:75], v[66:67], v[66:67]
	v_add_f32_e32 v0, v0, v73
	v_add_f32_e32 v0, v0, v74
	v_pk_mul_f32 v[76:77], v[26:27], v[26:27]
	v_add_f32_e32 v0, v0, v75
	v_add_f32_e32 v0, v0, v76
	v_pk_mul_f32 v[78:79], v[68:69], v[68:69]
	v_add_f32_e32 v0, v0, v77
	v_add_f32_e32 v0, v0, v78
	v_pk_mul_f32 v[80:81], v[28:29], v[28:29]
	v_add_f32_e32 v0, v0, v79
	v_add_f32_e32 v0, v0, v80
	v_pk_mul_f32 v[50:51], v[40:41], v[40:41]
	v_add_f32_e32 v0, v0, v81
	v_add_f32_e32 v0, v0, v50
	v_pk_mul_f32 v[52:53], v[30:31], v[30:31]
	v_add_f32_e32 v0, v0, v51
	v_add_f32_e32 v0, v0, v52
	v_pk_mul_f32 v[54:55], v[42:43], v[42:43]
	v_add_f32_e32 v0, v0, v53
	v_add_f32_e32 v0, v0, v54
	v_pk_mul_f32 v[56:57], v[18:19], v[18:19]
	v_add_f32_e32 v0, v0, v55
	v_add_f32_e32 v0, v0, v56
	v_pk_mul_f32 v[58:59], v[44:45], v[44:45]
	v_add_f32_e32 v0, v0, v57
	v_add_f32_e32 v0, v0, v58
	v_pk_mul_f32 v[60:61], v[22:23], v[22:23]
	v_add_f32_e32 v0, v0, v59
	v_add_f32_e32 v0, v0, v60
	v_pk_mul_f32 v[86:87], v[82:83], v[82:83]
	v_add_f32_e32 v0, v0, v61
	v_add_f32_e32 v0, v0, v86
	v_pk_mul_f32 v[98:99], v[84:85], v[84:85]
	v_add_f32_e32 v0, v0, v87
	v_add_f32_e32 v0, v0, v98
	v_add_f32_e32 v0, v0, v99
	ds_bpermute_b32 v50, v137, v0
	s_waitcnt lgkmcnt(0)
	v_add_f32_e32 v0, v0, v50
	v_fmamk_f32 v0, v0, 0x3c000000, v172
	v_mul_f32_e32 v50, 0x4b800000, v0
	v_cmp_gt_f32_e32 vcc, s8, v0
	s_nop 1
	v_cndmask_b32_e32 v0, v0, v50, vcc
	v_rsq_f32_e32 v50, v0
	v_lshlrev_b32_e32 v0, 2, v146
	v_lshl_add_u64 v[54:55], v[152:153], 0, v[0:1]
	v_mul_f32_e32 v0, 0x45800000, v50
	v_cndmask_b32_e32 v0, v50, v0, vcc
	v_mul_f32_e32 v0, v165, v0
	v_pk_mul_f32 v[50:51], v[88:89], v[0:1] op_sel_hi:[1,0]
	v_pk_mul_f32 v[20:21], v[20:21], v[0:1] op_sel_hi:[1,0]
	s_waitcnt lgkmcnt(0)
	ds_read_b128 v[234:237], v249 offset:32
	ds_read_b128 v[238:241], v249 offset:64
	ds_read_b128 v[242:245], v249 offset:96
	v_pk_mul_f32 v[50:51], v[62:63], v[50:51]
	v_pk_mul_f32 v[20:21], v[64:65], v[20:21]
	v_cvt_pk_bf16_f32 v250, v50, v51
	v_cvt_pk_bf16_f32 v251, v20, v21
	ds_read_b128 v[230:233], v249 offset:128
	v_pk_mul_f32 v[20:21], v[100:101], v[0:1] op_sel_hi:[1,0]
	v_pk_mul_f32 v[56:57], v[92:93], v[0:1] op_sel_hi:[1,0]
	v_pk_mul_f32 v[32:33], v[32:33], v[0:1] op_sel_hi:[1,0]
	v_pk_mul_f32 v[36:37], v[36:37], v[0:1] op_sel_hi:[1,0]
	v_pk_mul_f32 v[24:25], v[24:25], v[0:1] op_sel_hi:[1,0]
	v_pk_mul_f32 v[28:29], v[28:29], v[0:1] op_sel_hi:[1,0]
	v_pk_mul_f32 v[18:19], v[18:19], v[0:1] op_sel_hi:[1,0]
	v_pk_mul_f32 v[22:23], v[22:23], v[0:1] op_sel_hi:[1,0]
	s_waitcnt lgkmcnt(3)
; __device__ __forceinline__ unsigned pkbf(float lo, float hi) { f32x2 v = {lo, hi}; bf16x2v b = __builtin_convertvector(v, bf16x2v); return __builtin_bit_cast(unsigned, b); }
; __device__ __forceinline__ void attn_unit(const TI ti, CArgs& a, int b, int hd, int qrow0, int st_lo, int st_hi, float mfix, float lam, float lam_init, const float* subg, unsigned char* ldsg) {
;     ...
; #pragma unroll
;         for (int e = 0; e < 4; ++e)
; #pragma unroll
;             for (int g4 = 0; g4 < 4; ++g4) {
;                 const int e0 = e * 32 + 8 * g4 + 4 * h; const f32x4 sg = *(const f32x4*)(subg + e0);
;                 u32x2 o; o.x = pkbf(O[e][4 * g4 + 0] * sc * sg.x, O[e][4 * g4 + 1] * sc * sg.y); o.y = pkbf(O[e][4 * g4 + 2] * sc * sg.z, O[e][4 * g4 + 3] * sc * sg.w);
;                 *(u32x2*)(op + e0) = o;
;             }
	v_pk_mul_f32 v[20:21], v[234:235], v[20:21]
	v_pk_mul_f32 v[50:51], v[90:91], v[0:1] op_sel_hi:[1,0]
	v_cvt_pk_bf16_f32 v252, v20, v21
	v_pk_mul_f32 v[50:51], v[236:237], v[50:51]
	s_nop 0
	v_cvt_pk_bf16_f32 v253, v50, v51
	s_nop 1
	v_permlane32_swap_b32 v250, v252
	v_permlane32_swap_b32 v251, v253
	s_nop 0
	global_store_dwordx4 v[54:55], v[250:253], off
	ds_read_b128 v[234:237], v249 offset:160
	v_pk_mul_f32 v[20:21], v[110:111], v[0:1] op_sel_hi:[1,0]
	s_waitcnt lgkmcnt(3)
	v_pk_mul_f32 v[20:21], v[238:239], v[20:21]
	v_pk_mul_f32 v[50:51], v[240:241], v[56:57]
	v_cvt_pk_bf16_f32 v250, v20, v21
	v_cvt_pk_bf16_f32 v251, v50, v51
	ds_read_b128 v[238:241], v249 offset:192
	v_pk_mul_f32 v[20:21], v[112:113], v[0:1] op_sel_hi:[1,0]
	v_pk_mul_f32 v[56:57], v[94:95], v[0:1] op_sel_hi:[1,0]
	s_waitcnt lgkmcnt(3)
	v_pk_mul_f32 v[20:21], v[242:243], v[20:21]
	v_pk_mul_f32 v[50:51], v[244:245], v[56:57]
	v_cvt_pk_bf16_f32 v252, v20, v21
	v_cvt_pk_bf16_f32 v253, v50, v51
	s_nop 1
	v_permlane32_swap_b32 v250, v252
	v_permlane32_swap_b32 v251, v253
	s_nop 0
	global_store_dwordx4 v[54:55], v[250:253], off offset:32
	ds_read_b128 v[242:245], v249 offset:224
	v_pk_mul_f32 v[20:21], v[102:103], v[0:1] op_sel_hi:[1,0]
	v_pk_mul_f32 v[56:57], v[96:97], v[0:1] op_sel_hi:[1,0]
	s_waitcnt lgkmcnt(3)
	v_pk_mul_f32 v[20:21], v[230:231], v[20:21]
	v_pk_mul_f32 v[50:51], v[232:233], v[56:57]
	v_cvt_pk_bf16_f32 v250, v20, v21
	v_cvt_pk_bf16_f32 v251, v50, v51
	ds_read_b128 v[230:233], v249 offset:256
	v_pk_mul_f32 v[20:21], v[104:105], v[0:1] op_sel_hi:[1,0]
	s_waitcnt lgkmcnt(3)
	v_pk_mul_f32 v[32:33], v[236:237], v[32:33]
	v_pk_mul_f32 v[20:21], v[234:235], v[20:21]
	s_nop 0
	v_cvt_pk_bf16_f32 v252, v20, v21
	v_cvt_pk_bf16_f32 v253, v32, v33
	s_nop 1
	v_permlane32_swap_b32 v250, v252
	v_permlane32_swap_b32 v251, v253
	s_nop 0
	global_store_dwordx4 v[54:55], v[250:253], off offset:64
	ds_read_b128 v[234:237], v249 offset:288
	v_pk_mul_f32 v[20:21], v[106:107], v[0:1] op_sel_hi:[1,0]
	v_pk_mul_f32 v[32:33], v[34:35], v[0:1] op_sel_hi:[1,0]
	s_waitcnt lgkmcnt(3)
	v_pk_mul_f32 v[20:21], v[238:239], v[20:21]
	v_pk_mul_f32 v[32:33], v[240:241], v[32:33]
	v_cvt_pk_bf16_f32 v250, v20, v21
	v_cvt_pk_bf16_f32 v251, v32, v33
	ds_read_b128 v[238:241], v249 offset:320
	v_pk_mul_f32 v[20:21], v[108:109], v[0:1] op_sel_hi:[1,0]
	s_waitcnt lgkmcnt(3)
	v_pk_mul_f32 v[20:21], v[20:21], v[242:243]
	v_pk_mul_f32 v[32:33], v[36:37], v[244:245]
	v_cvt_pk_bf16_f32 v252, v20, v21
	v_cvt_pk_bf16_f32 v253, v32, v33
	s_nop 1
	v_permlane32_swap_b32 v250, v252
	v_permlane32_swap_b32 v251, v253
	s_nop 0
	global_store_dwordx4 v[54:55], v[250:253], off offset:96
	ds_read_b128 v[242:245], v249 offset:352
	v_pk_mul_f32 v[20:21], v[46:47], v[0:1] op_sel_hi:[1,0]
	v_pk_mul_f32 v[36:37], v[38:39], v[0:1] op_sel_hi:[1,0]
	s_waitcnt lgkmcnt(3)
	v_pk_mul_f32 v[20:21], v[20:21], v[230:231]
	v_pk_mul_f32 v[32:33], v[36:37], v[232:233]
	v_cvt_pk_bf16_f32 v250, v20, v21
	v_cvt_pk_bf16_f32 v251, v32, v33
	ds_read_b128 v[230:233], v249 offset:384
	v_pk_mul_f32 v[20:21], v[48:49], v[0:1] op_sel_hi:[1,0]
	s_waitcnt lgkmcnt(3)
	v_pk_mul_f32 v[24:25], v[24:25], v[236:237]
	v_pk_mul_f32 v[20:21], v[20:21], v[234:235]
	s_nop 0
	v_cvt_pk_bf16_f32 v252, v20, v21
	v_cvt_pk_bf16_f32 v253, v24, v25
	s_nop 1
	v_permlane32_swap_b32 v250, v252
	v_permlane32_swap_b32 v251, v253
	s_nop 0
	global_store_dwordx4 v[54:55], v[250:253], off offset:128
	ds_read_b128 v[234:237], v249 offset:416
	v_pk_mul_f32 v[20:21], v[66:67], v[0:1] op_sel_hi:[1,0]
	v_pk_mul_f32 v[24:25], v[26:27], v[0:1] op_sel_hi:[1,0]
	s_waitcnt lgkmcnt(3)
	v_pk_mul_f32 v[20:21], v[20:21], v[238:239]
	v_pk_mul_f32 v[24:25], v[24:25], v[240:241]
	v_cvt_pk_bf16_f32 v250, v20, v21
	v_cvt_pk_bf16_f32 v251, v24, v25
	ds_read_b128 v[238:241], v249 offset:448
	v_pk_mul_f32 v[20:21], v[68:69], v[0:1] op_sel_hi:[1,0]
	s_waitcnt lgkmcnt(3)
	v_pk_mul_f32 v[20:21], v[20:21], v[242:243]
	v_pk_mul_f32 v[24:25], v[28:29], v[244:245]
	v_cvt_pk_bf16_f32 v252, v20, v21
	v_cvt_pk_bf16_f32 v253, v24, v25
	s_nop 1
	v_permlane32_swap_b32 v250, v252
	v_permlane32_swap_b32 v251, v253
	s_nop 0
	global_store_dwordx4 v[54:55], v[250:253], off offset:160
	ds_read_b128 v[242:245], v249 offset:480
	v_pk_mul_f32 v[20:21], v[40:41], v[0:1] op_sel_hi:[1,0]
	v_pk_mul_f32 v[28:29], v[30:31], v[0:1] op_sel_hi:[1,0]
	s_waitcnt lgkmcnt(3)
	v_pk_mul_f32 v[20:21], v[20:21], v[230:231]
	v_pk_mul_f32 v[24:25], v[28:29], v[232:233]
	v_cvt_pk_bf16_f32 v250, v20, v21
	v_cvt_pk_bf16_f32 v251, v24, v25
	v_pk_mul_f32 v[20:21], v[42:43], v[0:1] op_sel_hi:[1,0]
	s_waitcnt lgkmcnt(2)
	v_pk_mul_f32 v[18:19], v[18:19], v[236:237]
	v_pk_mul_f32 v[20:21], v[20:21], v[234:235]
	v_pk_mul_f32 v[24:25], v[44:45], v[0:1] op_sel_hi:[1,0]
	v_cvt_pk_bf16_f32 v252, v20, v21
	v_cvt_pk_bf16_f32 v253, v18, v19
	s_nop 1
	v_permlane32_swap_b32 v250, v252
	v_permlane32_swap_b32 v251, v253
	s_nop 0
	global_store_dwordx4 v[54:55], v[250:253], off offset:192
	s_waitcnt lgkmcnt(1)
	v_pk_mul_f32 v[18:19], v[24:25], v[238:239]
	v_pk_mul_f32 v[20:21], v[22:23], v[240:241]
	v_cvt_pk_bf16_f32 v250, v18, v19
	v_cvt_pk_bf16_f32 v251, v20, v21
	v_pk_mul_f32 v[22:23], v[82:83], v[0:1] op_sel_hi:[1,0]
	v_pk_mul_f32 v[24:25], v[84:85], v[0:1] op_sel_hi:[1,0]
	s_waitcnt lgkmcnt(0)
	v_pk_mul_f32 v[18:19], v[22:23], v[242:243]
	v_pk_mul_f32 v[20:21], v[24:25], v[244:245]
	v_cvt_pk_bf16_f32 v252, v18, v19
	v_cvt_pk_bf16_f32 v253, v20, v21
	s_nop 1
	v_permlane32_swap_b32 v250, v252
	v_permlane32_swap_b32 v251, v253
	s_nop 0
	global_store_dwordx4 v[54:55], v[250:253], off offset:224
	s_branch .LBB0_331
